# v16 + XCD leader publishes the release word before its own L1 invalidate
# speedup vs baseline: 1.0218x; 1.0006x over previous
; __device__ __forceinline__ unsigned xb_ld(unsigned* p)              { return __hip_atomic_load(p, __ATOMIC_RELAXED, __HIP_MEMORY_SCOPE_AGENT); }
; __device__ __forceinline__ unsigned xb_add(unsigned* p, unsigned v) { return __hip_atomic_fetch_add(p, v, __ATOMIC_RELAXED, __HIP_MEMORY_SCOPE_AGENT); }
; #define XB_SPIN(cond, bar) do { unsigned _sp = 0; while (cond) { __builtin_amdgcn_s_sleep(1); \
;     if ((++_sp & 255u) == 0u) { if (xb_ld(&(bar)[XB_TMO])) break; if (_sp > XB_SPIN_CAP) { atomicAdd(&(bar)[XB_TMO], 1u); break; } } } } while (0)
; __device__ __forceinline__ void xcd_barrier(const XcdBarrier& b, int tid) {
;     ...
;             __builtin_amdgcn_fence(__ATOMIC_ACQUIRE, "agent");
;             xb_add(&bar[XB_XGEN(b.x)], 1u);
;             asm volatile("s_waitcnt vmcnt(0)" ::: "memory");
;         } else {
;             XB_SPIN(xb_ld(&bar[XB_XGEN(b.x)]) == gen, bar);
;             __builtin_amdgcn_fence(__ATOMIC_ACQUIRE, "agent");
;             asm volatile("s_waitcnt vmcnt(0)" ::: "memory");
.LBB0_362:
	s_or_b64 exec, exec, s[8:9]
	s_mov_b64 s[8:9], exec
	v_mbcnt_lo_u32_b32 v0, s8, 0
	v_mbcnt_hi_u32_b32 v0, s9, v0
	v_cmp_eq_u32_e32 vcc, 0, v0
	s_waitcnt vmcnt(0)
	s_and_saveexec_b64 s[10:11], vcc
	s_cbranch_execz .LBB0_364
	s_bcnt1_i32_b64 s0, s[8:9]
	v_mov_b32_e32 v0, 0x2000
	v_mov_b32_e32 v1, s0
	global_atomic_add v0, v1, s[6:7] offset:1024
.LBB0_364:
	s_or_b64 exec, exec, s[10:11]
	buffer_inv sc1
	s_waitcnt vmcnt(0)

; __device__ __forceinline__ unsigned xb_ld(unsigned* p)              { return __hip_atomic_load(p, __ATOMIC_RELAXED, __HIP_MEMORY_SCOPE_AGENT); }
; __device__ __forceinline__ unsigned xb_add(unsigned* p, unsigned v) { return __hip_atomic_fetch_add(p, v, __ATOMIC_RELAXED, __HIP_MEMORY_SCOPE_AGENT); }
; #define XB_SPIN(cond, bar) do { unsigned _sp = 0; while (cond) { __builtin_amdgcn_s_sleep(1); \
;     if ((++_sp & 255u) == 0u) { if (xb_ld(&(bar)[XB_TMO])) break; if (_sp > XB_SPIN_CAP) { atomicAdd(&(bar)[XB_TMO], 1u); break; } } } } while (0)
; __device__ __forceinline__ void xcd_barrier(const XcdBarrier& b, int tid) {
;     ...
;             __builtin_amdgcn_fence(__ATOMIC_ACQUIRE, "agent");
;             xb_add(&bar[XB_XGEN(b.x)], 1u);
;             asm volatile("s_waitcnt vmcnt(0)" ::: "memory");
;         } else {
;             XB_SPIN(xb_ld(&bar[XB_XGEN(b.x)]) == gen, bar);
;             __builtin_amdgcn_fence(__ATOMIC_ACQUIRE, "agent");
;             asm volatile("s_waitcnt vmcnt(0)" ::: "memory");
.LBB0_1040:
	s_or_b64 exec, exec, s[6:7]
	s_mov_b64 s[6:7], exec
	v_mbcnt_lo_u32_b32 v0, s6, 0
	v_mbcnt_hi_u32_b32 v0, s7, v0
	v_cmp_eq_u32_e32 vcc, 0, v0
	s_waitcnt vmcnt(0)
	s_and_saveexec_b64 s[8:9], vcc
	s_cbranch_execz .LBB0_1042
	s_bcnt1_i32_b64 s0, s[6:7]
	v_mov_b32_e32 v0, 0x2000
	v_mov_b32_e32 v1, s0
	global_atomic_add v0, v1, s[4:5] offset:1024
.LBB0_1042:
	s_or_b64 exec, exec, s[8:9]
	buffer_inv sc1
	s_waitcnt vmcnt(0)
